# 4-workgroup team barriers instead of grid barriers after 10 write-through GEMM phases (row-block producer/consumer team), plus scalar-base K-loop DMA addressing
# speedup vs baseline: 1.0358x; 1.0198x over previous
.LBB0_404:
	v_readlane_b32 s0, v243, 19
	v_readlane_b32 s22, v243, 20
	s_cmp_lg_u32 s0, 20
	s_mul_hi_u32 s16, s22, 0xcccccccd
	s_cselect_b64 s[0:1], -1, 0
	s_lshr_b32 s16, s16, 3
	s_mul_i32 s16, s16, 10
	s_sub_i32 s16, s22, s16
	s_cmp_lg_u32 s16, 6
	s_cselect_b64 s[22:23], -1, 0
	s_and_b64 s[0:1], s[0:1], s[22:23]
	s_andn2_b64 vcc, exec, s[0:1]
	s_cbranch_vccnz .LBB0_8
	s_waitcnt vmcnt(0)
	s_waitcnt vmcnt(0) lgkmcnt(0)
	s_barrier
	s_and_saveexec_b64 s[22:23], s[84:85]
	s_cbranch_execz .LBB0_7
	v_readlane_b32 s0, v243, 19
	s_mov_b32 s1, 0xc9f24
	s_lshr_b32 s1, s1, s0
	s_and_b32 s1, s1, 1
	s_cmp_eq_u32 s1, 0
	s_cbranch_scc1 .Ltb_full
	v_readlane_b32 s0, v243, 16
	s_and_b32 s0, s0, 63
	s_lshl_b32 s0, s0, 5
	s_add_u32 s28, s96, 0xeb12d00
	s_addc_u32 s29, s97, 0
	s_add_u32 s28, s28, s0
	s_addc_u32 s29, s29, 0
	s_add_u32 s34, s28, 0x1000
	s_addc_u32 s35, s29, 0
	v_mov_b32_e32 v1, 1
	global_atomic_add v2, v0, v1, s[28:29] sc0
	s_waitcnt vmcnt(0)
	v_readfirstlane_b32 s0, v2
	s_and_b32 s1, s0, 3
	s_lshr_b32 s0, s0, 2
	s_cmp_eq_u32 s1, 3
	s_cbranch_scc0 .Ltb_wait
	buffer_inv sc1
	global_atomic_add v0, v1, s[34:35]
	s_waitcnt vmcnt(0)
	s_branch .LBB0_7
.Ltb_wait:
	s_sleep 1
	global_load_dword v2, v0, s[34:35] sc1
	s_waitcnt vmcnt(0)
	v_readfirstlane_b32 s1, v2
	s_cmp_eq_u32 s1, s0
	s_cbranch_scc1 .Ltb_wait
	buffer_inv sc1
	s_waitcnt vmcnt(0)
	s_branch .LBB0_7
.Ltb_full:
	v_readlane_b32 s0, v248, 61
	s_waitcnt vmcnt(0) expcnt(0) lgkmcnt(0)
	s_nop 0
	v_mov_b32_e32 v1, s0
	ds_read_b32 v3, v1
	v_readlane_b32 s0, v248, 62
	s_waitcnt lgkmcnt(0)
	v_cmp_ne_u32_e32 vcc, 0, v3
	v_mov_b32_e32 v1, s0
	ds_read_b32 v2, v1
	s_cbranch_vccnz .LBB0_421
	s_mov_b32 s0, 1
	s_branch .LBB0_409
